# residual GEMM epilogues: f32 output stores with sc1 (agent-scope write-through) so the grid-barrier L2 writeback has less dirty data
# baseline (speedup 1.0000x reference)
;   DI void operator()(const pg8::f32x4 (&acc)[2][2][4][2], const pg8::Unit& u, int wr, int wc, int fr, int fq) const {
;     const int row0 = u.pm * 256 + wr * 64 + fr, col0 = u.pn * 256 + wc * 32 + 8 * fq;
;     const int b = (u.pm * 256) / TT;
; #pragma unroll
;     for (int ai = 0; ai < 2; ++ai)
; #pragma unroll
;       for (int m = 0; m < 4; ++m) {
;         const int row = row0 + ai * 128 + m * 16;
;         const int t = row - b * TT;
;         const bool isc = t >= TL;
;         float* dst = isc ? xc + ((size_t)b * TC + (t - TL)) * DM : xout + ((size_t)b * TL + t) * DM;
;         const float* src = src_input ? (isc ? cin + ((size_t)b * TC + (t - TL)) * DM : xin + ((size_t)b * TL + t) * DM) : dst;
;         const float* gate = modl + (size_t)(isc ? 16 : b) * 6144 + gi * DM;
; #pragma unroll
;         for (int bj = 0; bj < 2; ++bj) {
;           const int col = col0 + bj * 128;
; #pragma unroll
;           for (int n = 0; n < 2; ++n) {
;             pg8::f32x4 sv = *(const pg8::f32x4*)(src + col + 4 * n);
;             pg8::f32x4 gv = *(const pg8::f32x4*)(gate + col + 4 * n);
;             pg8::f32x4 o = sv + gv * acc[ai][bj][m][n];
;             *(pg8::f32x4*)(dst + col + 4 * n) = o;
;           }
;         }
;       }
;   }
.LBB0_1141:
	v_lshl_or_b32 v142, s30, 8, v150
	v_mov_b32_e32 v141, s34
	v_ashrrev_i32_e32 v143, 31, v142
	v_cndmask_b32_e64 v141, v141, 16, s[8:9]
	v_mov_b64_e32 v[154:155], s[20:21]
	s_movk_i32 s8, 0x6000
	v_lshlrev_b64 v[142:143], 2, v[142:143]
	v_mad_i64_i32 v[154:155], s[8:9], v141, s8, v[154:155]
	v_lshl_add_u64 v[162:163], v[146:147], 0, v[142:143]
	v_lshl_add_u64 v[164:165], v[154:155], 0, v[142:143]
	global_load_dwordx4 v[154:157], v[162:163], off
	global_load_dwordx4 v[158:161], v[164:165], off
	v_lshl_add_u64 v[166:167], v[144:145], 0, v[142:143]
	s_movk_i32 s8, 0x800
	v_add_u32_e32 v152, 0xfffff810, v140
	v_mov_b32_e32 v141, s25
	s_and_b64 vcc, exec, s[4:5]
	s_waitcnt vmcnt(0)
	v_pk_fma_f32 v[126:127], v[126:127], v[160:161], v[156:157]
	v_pk_fma_f32 v[124:125], v[124:125], v[158:159], v[154:155]
	global_store_dwordx4 v[166:167], v[124:127], off sc1
	global_load_dwordx4 v[124:127], v[162:163], off offset:16
	s_nop 0
	global_load_dwordx4 v[144:147], v[164:165], off offset:16
	s_waitcnt vmcnt(0)
	v_pk_fma_f32 v[122:123], v[122:123], v[146:147], v[126:127]
	v_pk_fma_f32 v[120:121], v[120:121], v[144:145], v[124:125]
	global_store_dwordx4 v[166:167], v[120:123], off offset:16 sc1
	global_load_dwordx4 v[120:123], v[162:163], off offset:512
	s_nop 0
	global_load_dwordx4 v[124:127], v[164:165], off offset:512
	v_mov_b32_e32 v144, s48
	v_mov_b32_e32 v146, s23
	v_mov_b32_e32 v147, s35
	s_waitcnt vmcnt(0)
	v_pk_fma_f32 v[118:119], v[118:119], v[126:127], v[122:123]
	v_pk_fma_f32 v[116:117], v[116:117], v[124:125], v[120:121]
	global_store_dwordx4 v[166:167], v[116:119], off offset:512 sc1
	global_load_dwordx4 v[120:123], v[162:163], off offset:528
	global_load_dwordx4 v[124:127], v[164:165], off offset:528
	v_or_b32_e32 v118, 16, v140
	v_cmp_gt_i32_e64 s[10:11], s8, v118
	s_movk_i32 s8, 0x7ff
	v_ashrrev_i32_e32 v119, 31, v118
	v_cmp_lt_i32_e64 s[8:9], s8, v118
	s_waitcnt vmcnt(0)
	v_pk_fma_f32 v[114:115], v[114:115], v[126:127], v[122:123]
	v_cndmask_b32_e64 v117, v119, 0, s[8:9]
	v_cndmask_b32_e64 v116, v118, v152, s[8:9]
	v_cndmask_b32_e64 v145, v141, v144, s[8:9]
	v_cndmask_b32_e64 v144, v146, v147, s[8:9]
	v_lshlrev_b64 v[116:117], 12, v[116:117]
	v_lshl_add_u64 v[116:117], v[144:145], 0, v[116:117]
	v_pk_fma_f32 v[112:113], v[112:113], v[124:125], v[120:121]
	global_store_dwordx4 v[166:167], v[112:115], off offset:528 sc1
	s_nop 1
	v_mov_b64_e32 v[112:113], v[116:117]
	s_cbranch_vccnz .LBB0_1147
	s_and_saveexec_b64 s[50:51], s[10:11]
	s_xor_b64 s[10:11], exec, s[50:51]
	s_add_u32 s50, s12, s38
	s_addc_u32 s51, s13, s39
	v_lshlrev_b64 v[112:113], 12, v[118:119]
	v_lshl_add_u64 v[112:113], s[50:51], 0, v[112:113]
	s_andn2_saveexec_b64 s[10:11], s[10:11]
	s_add_u32 s50, s14, s36
	s_addc_u32 s51, s15, s37
	v_lshlrev_b64 v[112:113], 12, v[152:153]
	v_lshl_add_u64 v[112:113], s[50:51], 0, v[112:113]
	s_or_b64 exec, exec, s[10:11]
.LBB0_1147:
	v_mov_b32_e32 v114, s34
	v_cndmask_b32_e64 v118, v114, 16, s[8:9]
	v_mov_b64_e32 v[114:115], s[20:21]
	s_movk_i32 s8, 0x6000
	v_mad_i64_i32 v[114:115], s[8:9], v118, s8, v[114:115]
	v_lshl_add_u64 v[122:123], v[112:113], 0, v[142:143]
	v_lshl_add_u64 v[124:125], v[114:115], 0, v[142:143]
	global_load_dwordx4 v[112:115], v[122:123], off
	global_load_dwordx4 v[118:121], v[124:125], off
	v_lshl_add_u64 v[116:117], v[116:117], 0, v[142:143]
	s_movk_i32 s8, 0x800
	v_add_u32_e32 v152, 0xfffff820, v140
	s_and_b64 vcc, exec, s[4:5]
	s_waitcnt vmcnt(0)
	v_pk_fma_f32 v[110:111], v[110:111], v[120:121], v[114:115]
	v_pk_fma_f32 v[108:109], v[108:109], v[118:119], v[112:113]
	global_store_dwordx4 v[116:117], v[108:111], off sc1
	global_load_dwordx4 v[108:111], v[122:123], off offset:16
	s_nop 0
	global_load_dwordx4 v[112:115], v[124:125], off offset:16
	s_waitcnt vmcnt(0)
	v_pk_fma_f32 v[106:107], v[106:107], v[114:115], v[110:111]
	v_pk_fma_f32 v[104:105], v[104:105], v[112:113], v[108:109]
	global_store_dwordx4 v[116:117], v[104:107], off offset:16 sc1
	global_load_dwordx4 v[104:107], v[122:123], off offset:512
	s_nop 0
	global_load_dwordx4 v[108:111], v[124:125], off offset:512
	v_mov_b32_e32 v112, s25
	v_mov_b32_e32 v113, s48
	v_mov_b32_e32 v114, s23
	v_mov_b32_e32 v115, s35
	s_waitcnt vmcnt(0)
	v_pk_fma_f32 v[102:103], v[102:103], v[110:111], v[106:107]
	v_pk_fma_f32 v[100:101], v[100:101], v[108:109], v[104:105]
	global_store_dwordx4 v[116:117], v[100:103], off offset:512 sc1
	global_load_dwordx4 v[104:107], v[122:123], off offset:528
	global_load_dwordx4 v[108:111], v[124:125], off offset:528
	v_or_b32_e32 v102, 32, v140
	v_cmp_gt_i32_e64 s[10:11], s8, v102
	s_movk_i32 s8, 0x7ff
	v_ashrrev_i32_e32 v103, 31, v102
	v_cmp_lt_i32_e64 s[8:9], s8, v102
	s_waitcnt vmcnt(0)
	v_pk_fma_f32 v[98:99], v[98:99], v[110:111], v[106:107]
	v_cndmask_b32_e64 v101, v103, 0, s[8:9]
	v_cndmask_b32_e64 v100, v102, v152, s[8:9]
	v_cndmask_b32_e64 v113, v112, v113, s[8:9]
	v_cndmask_b32_e64 v112, v114, v115, s[8:9]
	v_lshlrev_b64 v[100:101], 12, v[100:101]
	v_lshl_add_u64 v[100:101], v[112:113], 0, v[100:101]
	v_pk_fma_f32 v[96:97], v[96:97], v[108:109], v[104:105]
	global_store_dwordx4 v[116:117], v[96:99], off offset:528 sc1
	s_nop 1
	v_mov_b64_e32 v[96:97], v[100:101]
	s_cbranch_vccnz .LBB0_1153
	s_and_saveexec_b64 s[50:51], s[10:11]
	s_xor_b64 s[10:11], exec, s[50:51]
	s_add_u32 s50, s12, s38
	s_addc_u32 s51, s13, s39
	v_lshlrev_b64 v[96:97], 12, v[102:103]
	v_lshl_add_u64 v[96:97], s[50:51], 0, v[96:97]
	s_andn2_saveexec_b64 s[10:11], s[10:11]
	s_add_u32 s50, s14, s36
	s_addc_u32 s51, s15, s37
	v_lshlrev_b64 v[96:97], 12, v[152:153]
	v_lshl_add_u64 v[96:97], s[50:51], 0, v[96:97]
	s_or_b64 exec, exec, s[10:11]
;   DI void operator()(const pg8::f32x4 (&acc)[2][2][4][2], const pg8::Unit& u, int wr, int wc, int fr, int fq) const {
;     const int row0 = u.pm * 256 + wr * 64 + fr, col0 = u.pn * 256 + wc * 32 + 8 * fq;
;     const int b = (u.pm * 256) / TT;
; #pragma unroll
;     for (int ai = 0; ai < 2; ++ai)
; #pragma unroll
;       for (int m = 0; m < 4; ++m) {
;         const int row = row0 + ai * 128 + m * 16;
;         const int t = row - b * TT;
;         const bool isc = t >= TL;
;         float* dst = isc ? xc + ((size_t)b * TC + (t - TL)) * DM : xout + ((size_t)b * TL + t) * DM;
;         const float* src = src_input ? (isc ? cin + ((size_t)b * TC + (t - TL)) * DM : xin + ((size_t)b * TL + t) * DM) : dst;
;         const float* gate = modl + (size_t)(isc ? 16 : b) * 6144 + gi * DM;
; #pragma unroll
;         for (int bj = 0; bj < 2; ++bj) {
;           const int col = col0 + bj * 128;
; #pragma unroll
;           for (int n = 0; n < 2; ++n) {
;             pg8::f32x4 sv = *(const pg8::f32x4*)(src + col + 4 * n);
;             pg8::f32x4 gv = *(const pg8::f32x4*)(gate + col + 4 * n);
;             pg8::f32x4 o = sv + gv * acc[ai][bj][m][n];
;             *(pg8::f32x4*)(dst + col + 4 * n) = o;
;           }
;         }
;       }
;   }
.LBB0_1153:
	v_mov_b32_e32 v98, s34
	v_cndmask_b32_e64 v102, v98, 16, s[8:9]
	v_mov_b64_e32 v[98:99], s[20:21]
	s_movk_i32 s8, 0x6000
	v_mad_i64_i32 v[98:99], s[8:9], v102, s8, v[98:99]
	v_lshl_add_u64 v[106:107], v[96:97], 0, v[142:143]
	v_lshl_add_u64 v[108:109], v[98:99], 0, v[142:143]
	global_load_dwordx4 v[96:99], v[106:107], off
	global_load_dwordx4 v[102:105], v[108:109], off
	v_lshl_add_u64 v[100:101], v[100:101], 0, v[142:143]
	s_movk_i32 s8, 0x800
	v_add_u32_e32 v152, 0xfffff830, v140
	s_and_b64 vcc, exec, s[4:5]
	s_waitcnt vmcnt(0)
	v_pk_fma_f32 v[94:95], v[94:95], v[104:105], v[98:99]
	v_pk_fma_f32 v[92:93], v[92:93], v[102:103], v[96:97]
	global_store_dwordx4 v[100:101], v[92:95], off sc1
	global_load_dwordx4 v[92:95], v[106:107], off offset:16
	s_nop 0
	global_load_dwordx4 v[96:99], v[108:109], off offset:16
	s_waitcnt vmcnt(0)
	v_pk_fma_f32 v[90:91], v[90:91], v[98:99], v[94:95]
	v_pk_fma_f32 v[88:89], v[88:89], v[96:97], v[92:93]
	global_store_dwordx4 v[100:101], v[88:91], off offset:16 sc1
	global_load_dwordx4 v[88:91], v[106:107], off offset:512
	s_nop 0
	global_load_dwordx4 v[92:95], v[108:109], off offset:512
	v_mov_b32_e32 v96, s25
	v_mov_b32_e32 v97, s48
	v_mov_b32_e32 v98, s23
	v_mov_b32_e32 v99, s35
	s_waitcnt vmcnt(0)
	v_pk_fma_f32 v[86:87], v[86:87], v[94:95], v[90:91]
	v_pk_fma_f32 v[84:85], v[84:85], v[92:93], v[88:89]
	global_store_dwordx4 v[100:101], v[84:87], off offset:512 sc1
	global_load_dwordx4 v[88:91], v[106:107], off offset:528
	global_load_dwordx4 v[92:95], v[108:109], off offset:528
	v_or_b32_e32 v86, 48, v140
	v_cmp_gt_i32_e64 s[10:11], s8, v86
	s_movk_i32 s8, 0x7ff
	v_ashrrev_i32_e32 v87, 31, v86
	v_cmp_lt_i32_e64 s[8:9], s8, v86
	s_waitcnt vmcnt(0)
	v_pk_fma_f32 v[82:83], v[82:83], v[94:95], v[90:91]
	v_cndmask_b32_e64 v85, v87, 0, s[8:9]
	v_cndmask_b32_e64 v84, v86, v152, s[8:9]
	v_cndmask_b32_e64 v97, v96, v97, s[8:9]
	v_cndmask_b32_e64 v96, v98, v99, s[8:9]
	v_lshlrev_b64 v[84:85], 12, v[84:85]
	v_lshl_add_u64 v[84:85], v[96:97], 0, v[84:85]
	v_pk_fma_f32 v[80:81], v[80:81], v[92:93], v[88:89]
	global_store_dwordx4 v[100:101], v[80:83], off offset:528 sc1
	s_nop 1
	v_mov_b64_e32 v[80:81], v[84:85]
	s_cbranch_vccnz .LBB0_1159
	s_and_saveexec_b64 s[50:51], s[10:11]
	s_xor_b64 s[10:11], exec, s[50:51]
	s_add_u32 s50, s12, s38
	s_addc_u32 s51, s13, s39
	v_lshlrev_b64 v[80:81], 12, v[86:87]
	v_lshl_add_u64 v[80:81], s[50:51], 0, v[80:81]
	s_andn2_saveexec_b64 s[10:11], s[10:11]
	s_add_u32 s50, s14, s36
	s_addc_u32 s51, s15, s37
	v_lshlrev_b64 v[80:81], 12, v[152:153]
	v_lshl_add_u64 v[80:81], s[50:51], 0, v[80:81]
	s_or_b64 exec, exec, s[10:11]
.LBB0_1159:
	v_mov_b32_e32 v82, s34
	v_cndmask_b32_e64 v86, v82, 16, s[8:9]
	v_mov_b64_e32 v[82:83], s[20:21]
	s_movk_i32 s8, 0x6000
	v_mad_i64_i32 v[82:83], s[8:9], v86, s8, v[82:83]
	v_lshl_add_u64 v[90:91], v[80:81], 0, v[142:143]
	v_lshl_add_u64 v[92:93], v[82:83], 0, v[142:143]
	global_load_dwordx4 v[80:83], v[90:91], off
	global_load_dwordx4 v[86:89], v[92:93], off
	v_lshl_add_u64 v[84:85], v[84:85], 0, v[142:143]
	s_movk_i32 s8, 0x800
	v_add_u32_e32 v152, 0xfffff880, v140
	s_and_b64 vcc, exec, s[4:5]
	s_waitcnt vmcnt(0)
	v_pk_fma_f32 v[78:79], v[78:79], v[88:89], v[82:83]
	v_pk_fma_f32 v[76:77], v[76:77], v[86:87], v[80:81]
	global_store_dwordx4 v[84:85], v[76:79], off sc1
	global_load_dwordx4 v[76:79], v[90:91], off offset:16
	s_nop 0
	global_load_dwordx4 v[80:83], v[92:93], off offset:16
	s_waitcnt vmcnt(0)
	v_pk_fma_f32 v[74:75], v[74:75], v[82:83], v[78:79]
	v_pk_fma_f32 v[72:73], v[72:73], v[80:81], v[76:77]
	global_store_dwordx4 v[84:85], v[72:75], off offset:16 sc1
	global_load_dwordx4 v[72:75], v[90:91], off offset:512
	s_nop 0
	global_load_dwordx4 v[76:79], v[92:93], off offset:512
	v_mov_b32_e32 v80, s25
	v_mov_b32_e32 v81, s48
	v_mov_b32_e32 v82, s23
	v_mov_b32_e32 v83, s35
	s_waitcnt vmcnt(0)
	v_pk_fma_f32 v[70:71], v[70:71], v[78:79], v[74:75]
	v_pk_fma_f32 v[68:69], v[68:69], v[76:77], v[72:73]
	global_store_dwordx4 v[84:85], v[68:71], off offset:512 sc1
	global_load_dwordx4 v[72:75], v[90:91], off offset:528
	global_load_dwordx4 v[76:79], v[92:93], off offset:528
	v_add_u32_e32 v70, 0x80, v140
	v_cmp_gt_i32_e64 s[10:11], s8, v70
	s_movk_i32 s8, 0x7ff
	v_ashrrev_i32_e32 v71, 31, v70
	v_cmp_lt_i32_e64 s[8:9], s8, v70
	s_waitcnt vmcnt(0)
	v_pk_fma_f32 v[66:67], v[66:67], v[78:79], v[74:75]
	v_cndmask_b32_e64 v69, v71, 0, s[8:9]
	v_cndmask_b32_e64 v68, v70, v152, s[8:9]
	v_cndmask_b32_e64 v81, v80, v81, s[8:9]
	v_cndmask_b32_e64 v80, v82, v83, s[8:9]
	v_lshlrev_b64 v[68:69], 12, v[68:69]
	v_lshl_add_u64 v[68:69], v[80:81], 0, v[68:69]
	v_pk_fma_f32 v[64:65], v[64:65], v[76:77], v[72:73]
	global_store_dwordx4 v[84:85], v[64:67], off offset:528 sc1
	s_nop 1
	v_mov_b64_e32 v[64:65], v[68:69]
	s_cbranch_vccnz .LBB0_1165
	s_and_saveexec_b64 s[50:51], s[10:11]
	s_xor_b64 s[10:11], exec, s[50:51]
	s_add_u32 s50, s12, s38
	s_addc_u32 s51, s13, s39
	v_lshlrev_b64 v[64:65], 12, v[70:71]
	v_lshl_add_u64 v[64:65], s[50:51], 0, v[64:65]
	s_andn2_saveexec_b64 s[10:11], s[10:11]
	s_add_u32 s50, s14, s36
	s_addc_u32 s51, s15, s37
	v_lshlrev_b64 v[64:65], 12, v[152:153]
	v_lshl_add_u64 v[64:65], s[50:51], 0, v[64:65]
	s_or_b64 exec, exec, s[10:11]
;   DI void operator()(const pg8::f32x4 (&acc)[2][2][4][2], const pg8::Unit& u, int wr, int wc, int fr, int fq) const {
;     const int row0 = u.pm * 256 + wr * 64 + fr, col0 = u.pn * 256 + wc * 32 + 8 * fq;
;     const int b = (u.pm * 256) / TT;
; #pragma unroll
;     for (int ai = 0; ai < 2; ++ai)
; #pragma unroll
;       for (int m = 0; m < 4; ++m) {
;         const int row = row0 + ai * 128 + m * 16;
;         const int t = row - b * TT;
;         const bool isc = t >= TL;
;         float* dst = isc ? xc + ((size_t)b * TC + (t - TL)) * DM : xout + ((size_t)b * TL + t) * DM;
;         const float* src = src_input ? (isc ? cin + ((size_t)b * TC + (t - TL)) * DM : xin + ((size_t)b * TL + t) * DM) : dst;
;         const float* gate = modl + (size_t)(isc ? 16 : b) * 6144 + gi * DM;
; #pragma unroll
;         for (int bj = 0; bj < 2; ++bj) {
;           const int col = col0 + bj * 128;
; #pragma unroll
;           for (int n = 0; n < 2; ++n) {
;             pg8::f32x4 sv = *(const pg8::f32x4*)(src + col + 4 * n);
;             pg8::f32x4 gv = *(const pg8::f32x4*)(gate + col + 4 * n);
;             pg8::f32x4 o = sv + gv * acc[ai][bj][m][n];
;             *(pg8::f32x4*)(dst + col + 4 * n) = o;
;           }
;         }
;       }
;   }
.LBB0_1165:
	v_mov_b32_e32 v66, s34
	v_cndmask_b32_e64 v70, v66, 16, s[8:9]
	v_mov_b64_e32 v[66:67], s[20:21]
	s_movk_i32 s8, 0x6000
	v_mad_i64_i32 v[66:67], s[8:9], v70, s8, v[66:67]
	v_lshl_add_u64 v[74:75], v[64:65], 0, v[142:143]
	v_lshl_add_u64 v[76:77], v[66:67], 0, v[142:143]
	global_load_dwordx4 v[64:67], v[74:75], off
	global_load_dwordx4 v[70:73], v[76:77], off
	v_lshl_add_u64 v[68:69], v[68:69], 0, v[142:143]
	s_movk_i32 s8, 0x800
	v_add_u32_e32 v152, 0xfffff890, v140
	s_and_b64 vcc, exec, s[4:5]
	s_waitcnt vmcnt(0)
	v_pk_fma_f32 v[62:63], v[62:63], v[72:73], v[66:67]
	v_pk_fma_f32 v[60:61], v[60:61], v[70:71], v[64:65]
	global_store_dwordx4 v[68:69], v[60:63], off sc1
	global_load_dwordx4 v[60:63], v[74:75], off offset:16
	s_nop 0
	global_load_dwordx4 v[64:67], v[76:77], off offset:16
	s_waitcnt vmcnt(0)
	v_pk_fma_f32 v[58:59], v[58:59], v[66:67], v[62:63]
	v_pk_fma_f32 v[56:57], v[56:57], v[64:65], v[60:61]
	global_store_dwordx4 v[68:69], v[56:59], off offset:16 sc1
	global_load_dwordx4 v[56:59], v[74:75], off offset:512
	s_nop 0
	global_load_dwordx4 v[60:63], v[76:77], off offset:512
	v_mov_b32_e32 v64, s25
	v_mov_b32_e32 v65, s48
	v_mov_b32_e32 v66, s23
	v_mov_b32_e32 v67, s35
	s_waitcnt vmcnt(0)
	v_pk_fma_f32 v[54:55], v[54:55], v[62:63], v[58:59]
	v_pk_fma_f32 v[52:53], v[52:53], v[60:61], v[56:57]
	global_store_dwordx4 v[68:69], v[52:55], off offset:512 sc1
	global_load_dwordx4 v[56:59], v[74:75], off offset:528
	global_load_dwordx4 v[60:63], v[76:77], off offset:528
	v_add_u32_e32 v54, 0x90, v140
	v_cmp_gt_i32_e64 s[10:11], s8, v54
	s_movk_i32 s8, 0x7ff
	v_ashrrev_i32_e32 v55, 31, v54
	v_cmp_lt_i32_e64 s[8:9], s8, v54
	s_waitcnt vmcnt(0)
	v_pk_fma_f32 v[50:51], v[50:51], v[62:63], v[58:59]
	v_cndmask_b32_e64 v53, v55, 0, s[8:9]
	v_cndmask_b32_e64 v52, v54, v152, s[8:9]
	v_cndmask_b32_e64 v65, v64, v65, s[8:9]
	v_cndmask_b32_e64 v64, v66, v67, s[8:9]
	v_lshlrev_b64 v[52:53], 12, v[52:53]
	v_lshl_add_u64 v[52:53], v[64:65], 0, v[52:53]
	v_pk_fma_f32 v[48:49], v[48:49], v[60:61], v[56:57]
	global_store_dwordx4 v[68:69], v[48:51], off offset:528 sc1
	s_nop 1
	v_mov_b64_e32 v[48:49], v[52:53]
	s_cbranch_vccnz .LBB0_1171
	s_and_saveexec_b64 s[50:51], s[10:11]
	s_xor_b64 s[10:11], exec, s[50:51]
	s_add_u32 s50, s12, s38
	s_addc_u32 s51, s13, s39
	v_lshlrev_b64 v[48:49], 12, v[54:55]
	v_lshl_add_u64 v[48:49], s[50:51], 0, v[48:49]
	s_andn2_saveexec_b64 s[10:11], s[10:11]
	s_add_u32 s50, s14, s36
	s_addc_u32 s51, s15, s37
	v_lshlrev_b64 v[48:49], 12, v[152:153]
	v_lshl_add_u64 v[48:49], s[50:51], 0, v[48:49]
	s_or_b64 exec, exec, s[10:11]
.LBB0_1171:
	v_mov_b32_e32 v50, s34
	v_cndmask_b32_e64 v54, v50, 16, s[8:9]
	v_mov_b64_e32 v[50:51], s[20:21]
	s_movk_i32 s8, 0x6000
	v_mad_i64_i32 v[50:51], s[8:9], v54, s8, v[50:51]
	v_lshl_add_u64 v[58:59], v[48:49], 0, v[142:143]
	v_lshl_add_u64 v[60:61], v[50:51], 0, v[142:143]
	global_load_dwordx4 v[48:51], v[58:59], off
	global_load_dwordx4 v[54:57], v[60:61], off
	v_lshl_add_u64 v[52:53], v[52:53], 0, v[142:143]
	s_movk_i32 s8, 0x800
	v_add_u32_e32 v152, 0xfffff8a0, v140
	s_and_b64 vcc, exec, s[4:5]
	s_waitcnt vmcnt(0)
	v_pk_fma_f32 v[46:47], v[46:47], v[56:57], v[50:51]
	v_pk_fma_f32 v[44:45], v[44:45], v[54:55], v[48:49]
	global_store_dwordx4 v[52:53], v[44:47], off sc1
	global_load_dwordx4 v[44:47], v[58:59], off offset:16
	s_nop 0
	global_load_dwordx4 v[48:51], v[60:61], off offset:16
	s_waitcnt vmcnt(0)
	v_pk_fma_f32 v[42:43], v[42:43], v[50:51], v[46:47]
	v_pk_fma_f32 v[40:41], v[40:41], v[48:49], v[44:45]
	global_store_dwordx4 v[52:53], v[40:43], off offset:16 sc1
	global_load_dwordx4 v[40:43], v[58:59], off offset:512
	s_nop 0
	global_load_dwordx4 v[44:47], v[60:61], off offset:512
	v_mov_b32_e32 v48, s25
	v_mov_b32_e32 v49, s48
	v_mov_b32_e32 v50, s23
	v_mov_b32_e32 v51, s35
	s_waitcnt vmcnt(0)
	v_pk_fma_f32 v[38:39], v[38:39], v[46:47], v[42:43]
	v_pk_fma_f32 v[36:37], v[36:37], v[44:45], v[40:41]
	global_store_dwordx4 v[52:53], v[36:39], off offset:512 sc1
	global_load_dwordx4 v[40:43], v[58:59], off offset:528
	global_load_dwordx4 v[44:47], v[60:61], off offset:528
	v_add_u32_e32 v38, 0xa0, v140
	v_cmp_gt_i32_e64 s[10:11], s8, v38
	s_movk_i32 s8, 0x7ff
	v_ashrrev_i32_e32 v39, 31, v38
	v_cmp_lt_i32_e64 s[8:9], s8, v38
	s_waitcnt vmcnt(0)
	v_pk_fma_f32 v[34:35], v[34:35], v[46:47], v[42:43]
	v_cndmask_b32_e64 v37, v39, 0, s[8:9]
	v_cndmask_b32_e64 v36, v38, v152, s[8:9]
	v_cndmask_b32_e64 v49, v48, v49, s[8:9]
	v_cndmask_b32_e64 v48, v50, v51, s[8:9]
	v_lshlrev_b64 v[36:37], 12, v[36:37]
	v_lshl_add_u64 v[36:37], v[48:49], 0, v[36:37]
	v_pk_fma_f32 v[32:33], v[32:33], v[44:45], v[40:41]
	global_store_dwordx4 v[52:53], v[32:35], off offset:528 sc1
	s_nop 1
	v_mov_b64_e32 v[32:33], v[36:37]
	s_cbranch_vccnz .LBB0_1177
	s_and_saveexec_b64 s[50:51], s[10:11]
	s_xor_b64 s[10:11], exec, s[50:51]
	s_add_u32 s50, s12, s38
	s_addc_u32 s51, s13, s39
	v_lshlrev_b64 v[32:33], 12, v[38:39]
	v_lshl_add_u64 v[32:33], s[50:51], 0, v[32:33]
	s_andn2_saveexec_b64 s[10:11], s[10:11]
	s_add_u32 s50, s14, s36
	s_addc_u32 s51, s15, s37
	v_lshlrev_b64 v[32:33], 12, v[152:153]
	v_lshl_add_u64 v[32:33], s[50:51], 0, v[32:33]
	s_or_b64 exec, exec, s[10:11]
;   DI void operator()(const pg8::f32x4 (&acc)[2][2][4][2], const pg8::Unit& u, int wr, int wc, int fr, int fq) const {
;     const int row0 = u.pm * 256 + wr * 64 + fr, col0 = u.pn * 256 + wc * 32 + 8 * fq;
;     const int b = (u.pm * 256) / TT;
; #pragma unroll
;     for (int ai = 0; ai < 2; ++ai)
; #pragma unroll
;       for (int m = 0; m < 4; ++m) {
;         const int row = row0 + ai * 128 + m * 16;
;         const int t = row - b * TT;
;         const bool isc = t >= TL;
;         float* dst = isc ? xc + ((size_t)b * TC + (t - TL)) * DM : xout + ((size_t)b * TL + t) * DM;
;         const float* src = src_input ? (isc ? cin + ((size_t)b * TC + (t - TL)) * DM : xin + ((size_t)b * TL + t) * DM) : dst;
;         const float* gate = modl + (size_t)(isc ? 16 : b) * 6144 + gi * DM;
; #pragma unroll
;         for (int bj = 0; bj < 2; ++bj) {
;           const int col = col0 + bj * 128;
; #pragma unroll
;           for (int n = 0; n < 2; ++n) {
;             pg8::f32x4 sv = *(const pg8::f32x4*)(src + col + 4 * n);
;             pg8::f32x4 gv = *(const pg8::f32x4*)(gate + col + 4 * n);
;             pg8::f32x4 o = sv + gv * acc[ai][bj][m][n];
;             *(pg8::f32x4*)(dst + col + 4 * n) = o;
;           }
;         }
;       }
;   }
.LBB0_1177:
	v_mov_b32_e32 v34, s34
	v_cndmask_b32_e64 v38, v34, 16, s[8:9]
	v_mov_b64_e32 v[34:35], s[20:21]
	s_movk_i32 s8, 0x6000
	v_mad_i64_i32 v[34:35], s[8:9], v38, s8, v[34:35]
	v_lshl_add_u64 v[42:43], v[32:33], 0, v[142:143]
	v_lshl_add_u64 v[44:45], v[34:35], 0, v[142:143]
	global_load_dwordx4 v[32:35], v[42:43], off
	global_load_dwordx4 v[38:41], v[44:45], off
	v_lshl_add_u64 v[36:37], v[36:37], 0, v[142:143]
	s_and_b64 vcc, exec, s[4:5]
	s_movk_i32 s4, 0x800
	v_add_u32_e32 v152, 0xfffff8b0, v140
	s_waitcnt vmcnt(0)
	v_pk_fma_f32 v[30:31], v[30:31], v[40:41], v[34:35]
	v_pk_fma_f32 v[28:29], v[28:29], v[38:39], v[32:33]
	global_store_dwordx4 v[36:37], v[28:31], off sc1
	global_load_dwordx4 v[28:31], v[42:43], off offset:16
	s_nop 0
	global_load_dwordx4 v[32:35], v[44:45], off offset:16
	s_waitcnt vmcnt(0)
	v_pk_fma_f32 v[26:27], v[26:27], v[34:35], v[30:31]
	v_pk_fma_f32 v[24:25], v[24:25], v[32:33], v[28:29]
	global_store_dwordx4 v[36:37], v[24:27], off offset:16 sc1
	global_load_dwordx4 v[24:27], v[42:43], off offset:512
	s_nop 0
	global_load_dwordx4 v[28:31], v[44:45], off offset:512
	v_mov_b32_e32 v32, s25
	v_mov_b32_e32 v33, s48
	v_mov_b32_e32 v34, s23
	v_mov_b32_e32 v35, s35
	s_waitcnt vmcnt(0)
	v_pk_fma_f32 v[22:23], v[22:23], v[30:31], v[26:27]
	v_pk_fma_f32 v[20:21], v[20:21], v[28:29], v[24:25]
	global_store_dwordx4 v[36:37], v[20:23], off offset:512 sc1
	global_load_dwordx4 v[24:27], v[42:43], off offset:528
	global_load_dwordx4 v[28:31], v[44:45], off offset:528
	v_add_u32_e32 v22, 0xb0, v140
	v_cmp_gt_i32_e64 s[8:9], s4, v22
	s_movk_i32 s4, 0x7ff
	v_ashrrev_i32_e32 v23, 31, v22
	v_cmp_lt_i32_e64 s[4:5], s4, v22
	s_waitcnt vmcnt(0)
	v_pk_fma_f32 v[18:19], v[18:19], v[30:31], v[26:27]
	v_cndmask_b32_e64 v21, v23, 0, s[4:5]
	v_cndmask_b32_e64 v20, v22, v152, s[4:5]
	v_cndmask_b32_e64 v33, v32, v33, s[4:5]
	v_cndmask_b32_e64 v32, v34, v35, s[4:5]
	v_lshlrev_b64 v[20:21], 12, v[20:21]
	v_lshl_add_u64 v[20:21], v[32:33], 0, v[20:21]
	v_pk_fma_f32 v[16:17], v[16:17], v[28:29], v[24:25]
	global_store_dwordx4 v[36:37], v[16:19], off offset:528 sc1
	s_nop 1
	v_mov_b64_e32 v[16:17], v[20:21]
	s_cbranch_vccnz .LBB0_1183
	s_and_saveexec_b64 s[10:11], s[8:9]
	s_xor_b64 s[8:9], exec, s[10:11]
	s_add_u32 s10, s12, s38
	s_addc_u32 s11, s13, s39
	v_lshlrev_b64 v[16:17], 12, v[22:23]
	v_lshl_add_u64 v[16:17], s[10:11], 0, v[16:17]
	s_andn2_saveexec_b64 s[8:9], s[8:9]
	s_add_u32 s10, s14, s36
	s_addc_u32 s11, s15, s37
	v_lshlrev_b64 v[16:17], 12, v[152:153]
	v_lshl_add_u64 v[16:17], s[10:11], 0, v[16:17]
	s_or_b64 exec, exec, s[8:9]
.LBB0_1183:
	v_mov_b32_e32 v18, s34
	v_cndmask_b32_e64 v22, v18, 16, s[4:5]
	v_mov_b64_e32 v[18:19], s[20:21]
	s_movk_i32 s4, 0x6000
	v_mad_i64_i32 v[18:19], s[4:5], v22, s4, v[18:19]
	v_lshl_add_u64 v[24:25], v[16:17], 0, v[142:143]
	v_lshl_add_u64 v[26:27], v[18:19], 0, v[142:143]
	v_lshl_add_u64 v[28:29], v[20:21], 0, v[142:143]
	global_load_dwordx4 v[16:19], v[24:25], off
	global_load_dwordx4 v[20:23], v[26:27], off
	s_mov_b64 s[4:5], -1
	s_andn2_b64 vcc, exec, s[2:3]
	s_waitcnt vmcnt(0)
	v_pk_fma_f32 v[14:15], v[14:15], v[22:23], v[18:19]
	v_pk_fma_f32 v[12:13], v[12:13], v[20:21], v[16:17]
	global_store_dwordx4 v[28:29], v[12:15], off sc1
	global_load_dwordx4 v[12:15], v[24:25], off offset:16
	s_nop 0
	global_load_dwordx4 v[16:19], v[26:27], off offset:16
	s_waitcnt vmcnt(0)
	v_pk_fma_f32 v[10:11], v[10:11], v[18:19], v[14:15]
	v_pk_fma_f32 v[8:9], v[8:9], v[16:17], v[12:13]
	global_store_dwordx4 v[28:29], v[8:11], off offset:16 sc1
	global_load_dwordx4 v[8:11], v[24:25], off offset:512
	s_nop 0
	global_load_dwordx4 v[12:15], v[26:27], off offset:512
	s_waitcnt vmcnt(0)
	v_pk_fma_f32 v[6:7], v[6:7], v[14:15], v[10:11]
	v_pk_fma_f32 v[4:5], v[4:5], v[12:13], v[8:9]
	global_store_dwordx4 v[28:29], v[4:7], off offset:512 sc1
	global_load_dwordx4 v[4:7], v[24:25], off offset:528
	s_nop 0
	global_load_dwordx4 v[8:11], v[26:27], off offset:528
	s_waitcnt vmcnt(0)
	v_pk_fma_f32 v[2:3], v[2:3], v[10:11], v[6:7]
	v_pk_fma_f32 v[0:1], v[0:1], v[8:9], v[4:5]
	global_store_dwordx4 v[28:29], v[0:3], off offset:528 sc1
	s_cbranch_vccnz .LBB0_1128
	s_andn2_b64 vcc, exec, s[16:17]
	s_cbranch_vccnz .LBB0_1127
	s_barrier
	s_branch .LBB0_1127

;   DI void operator()(const pg8::f32x4 (&acc)[2][2][4][2], const pg8::Unit& u, int wr, int wc, int fr, int fq) const {
;     const int row0 = u.pm * 256 + wr * 64 + fr, col0 = u.pn * 256 + wc * 32 + 8 * fq;
;     const int b = (u.pm * 256) / TT;
; #pragma unroll
;     for (int ai = 0; ai < 2; ++ai)
; #pragma unroll
;       for (int m = 0; m < 4; ++m) {
;         const int row = row0 + ai * 128 + m * 16;
;         const int t = row - b * TT;
;         const bool isc = t >= TL;
;         float* dst = isc ? xc + ((size_t)b * TC + (t - TL)) * DM : xout + ((size_t)b * TL + t) * DM;
;         const float* src = src_input ? (isc ? cin + ((size_t)b * TC + (t - TL)) * DM : xin + ((size_t)b * TL + t) * DM) : dst;
;         const float* gate = modl + (size_t)(isc ? 16 : b) * 6144 + gi * DM;
; #pragma unroll
;         for (int bj = 0; bj < 2; ++bj) {
;           const int col = col0 + bj * 128;
; #pragma unroll
;           for (int n = 0; n < 2; ++n) {
;             pg8::f32x4 sv = *(const pg8::f32x4*)(src + col + 4 * n);
;             pg8::f32x4 gv = *(const pg8::f32x4*)(gate + col + 4 * n);
;             pg8::f32x4 o = sv + gv * acc[ai][bj][m][n];
;             *(pg8::f32x4*)(dst + col + 4 * n) = o;
;           }
;         }
;       }
;   }
.LBB0_1507:
	s_mov_b32 s4, 0x38e38e39
	v_mul_hi_i32 v142, v148, s4
	v_lshrrev_b32_e32 v144, 31, v142
	v_ashrrev_i32_e32 v142, 1, v142
	v_add_u32_e32 v142, v142, v144
	s_movk_i32 s4, 0xf700
	s_load_dwordx4 s[24:27], s[0:1], 0x100
	v_lshlrev_b32_e32 v143, 8, v148
	v_mul_lo_u32 v144, v142, s4
	v_add_u32_e32 v143, v144, v143
	v_add_u32_e32 v160, v143, v154
	v_ashrrev_i32_e32 v143, 31, v142
	v_readlane_b32 s4, v252, 14
	s_movk_i32 s21, 0x7ff
	v_lshlrev_b64 v[144:145], 23, v[142:143]
	v_lshlrev_b64 v[146:147], 20, v[142:143]
	v_ashrrev_i32_e32 v143, 31, v160
	v_add_u32_e32 v148, 0xfffff800, v160
	v_readlane_b32 s5, v252, 15
	v_cmp_lt_i32_e32 vcc, s21, v160
	v_lshl_or_b32 v150, v149, 8, v156
	s_waitcnt lgkmcnt(0)
	v_lshl_add_u64 v[144:145], s[24:25], 0, v[144:145]
	v_lshl_add_u64 v[146:147], s[4:5], 0, v[146:147]
	v_cndmask_b32_e64 v149, v143, 0, vcc
	v_cndmask_b32_e32 v148, v160, v148, vcc
	v_cndmask_b32_e32 v163, v145, v147, vcc
	v_cndmask_b32_e32 v162, v144, v146, vcc
	v_lshlrev_b64 v[148:149], 12, v[148:149]
	v_lshl_add_u64 v[162:163], v[162:163], 0, v[148:149]
	v_cndmask_b32_e64 v143, v142, 16, vcc
	v_mov_b64_e32 v[148:149], s[10:11]
	s_movk_i32 s22, 0x6000
	v_ashrrev_i32_e32 v151, 31, v150
	v_mad_i64_i32 v[164:165], s[4:5], v143, s22, v[148:149]
	v_lshlrev_b64 v[150:151], 2, v[150:151]
	v_lshl_add_u64 v[176:177], v[164:165], 0, v[150:151]
	v_lshl_add_u64 v[174:175], v[162:163], 0, v[150:151]
	s_mov_b64 s[4:5], 0x10000
	s_mov_b64 s[24:25], 0x50000
	global_load_dwordx4 v[202:205], v[176:177], off
	global_load_dwordx4 v[206:209], v[176:177], off offset:16
	global_load_dwordx4 v[210:213], v[176:177], off offset:512
	global_load_dwordx4 v[214:217], v[176:177], off offset:528
	global_load_dwordx4 v[218:221], v[174:175], off
	global_load_dwordx4 v[222:225], v[174:175], off offset:16
	global_load_dwordx4 v[226:229], v[174:175], off offset:512
	global_load_dwordx4 v[230:233], v[174:175], off offset:528
	v_lshl_add_u64 v[142:143], v[174:175], 0, s[4:5]
	global_load_dwordx4 v[234:237], v[142:143], off
	global_load_dwordx4 v[238:241], v[142:143], off offset:16
	global_load_dwordx4 v[242:245], v[142:143], off offset:512
	global_load_dwordx4 v[246:249], v[142:143], off offset:528
	v_lshl_add_u64 v[144:145], v[142:143], 0, s[4:5]
	global_load_dwordx4 v[160:163], v[144:145], off
	global_load_dwordx4 v[164:167], v[144:145], off offset:16
	global_load_dwordx4 v[168:171], v[144:145], off offset:512
	global_load_dwordx4 v[178:181], v[144:145], off offset:528
	v_lshl_add_u64 v[146:147], v[144:145], 0, s[4:5]
	v_lshl_add_u64 v[148:149], v[146:147], 0, s[24:25]
	v_lshl_add_u64 v[150:151], v[148:149], 0, s[4:5]
	v_lshl_add_u64 v[192:193], v[150:151], 0, s[4:5]
	v_lshl_add_u64 v[194:195], v[192:193], 0, s[4:5]
	s_waitcnt vmcnt(8)
	v_pk_fma_f32 v[126:127], v[126:127], v[204:205], v[220:221]
	v_pk_fma_f32 v[124:125], v[124:125], v[202:203], v[218:219]
	v_pk_fma_f32 v[122:123], v[122:123], v[208:209], v[224:225]
	v_pk_fma_f32 v[120:121], v[120:121], v[206:207], v[222:223]
	v_pk_fma_f32 v[118:119], v[118:119], v[212:213], v[228:229]
	v_pk_fma_f32 v[116:117], v[116:117], v[210:211], v[226:227]
	v_pk_fma_f32 v[106:107], v[106:107], v[216:217], v[232:233]
	v_pk_fma_f32 v[104:105], v[104:105], v[214:215], v[230:231]
	global_store_dwordx4 v[174:175], v[124:127], off sc1
	global_store_dwordx4 v[174:175], v[120:123], off offset:16 sc1
	global_store_dwordx4 v[174:175], v[116:119], off offset:512 sc1
	global_store_dwordx4 v[174:175], v[104:107], off offset:528 sc1
	global_load_dwordx4 v[218:221], v[146:147], off
	global_load_dwordx4 v[222:225], v[146:147], off offset:16
	global_load_dwordx4 v[226:229], v[146:147], off offset:512
	global_load_dwordx4 v[230:233], v[146:147], off offset:528
	s_waitcnt vmcnt(12)
	v_pk_fma_f32 v[114:115], v[114:115], v[204:205], v[236:237]
	v_pk_fma_f32 v[112:113], v[112:113], v[202:203], v[234:235]
	v_pk_fma_f32 v[110:111], v[110:111], v[208:209], v[240:241]
	v_pk_fma_f32 v[108:109], v[108:109], v[206:207], v[238:239]
	v_pk_fma_f32 v[102:103], v[102:103], v[212:213], v[244:245]
	v_pk_fma_f32 v[100:101], v[100:101], v[210:211], v[242:243]
	v_pk_fma_f32 v[90:91], v[90:91], v[216:217], v[248:249]
	v_pk_fma_f32 v[88:89], v[88:89], v[214:215], v[246:247]
	global_store_dwordx4 v[142:143], v[112:115], off sc1
	global_store_dwordx4 v[142:143], v[108:111], off offset:16 sc1
	global_store_dwordx4 v[142:143], v[100:103], off offset:512 sc1
	global_store_dwordx4 v[142:143], v[88:91], off offset:528 sc1
	global_load_dwordx4 v[234:237], v[148:149], off
	global_load_dwordx4 v[238:241], v[148:149], off offset:16
	global_load_dwordx4 v[242:245], v[148:149], off offset:512
	global_load_dwordx4 v[246:249], v[148:149], off offset:528
	s_waitcnt vmcnt(16)
;   DI void operator()(const pg8::f32x4 (&acc)[2][2][4][2], const pg8::Unit& u, int wr, int wc, int fr, int fq) const {
;     const int row0 = u.pm * 256 + wr * 64 + fr, col0 = u.pn * 256 + wc * 32 + 8 * fq;
;     const int b = (u.pm * 256) / TT;
; #pragma unroll
;     for (int ai = 0; ai < 2; ++ai)
; #pragma unroll
;       for (int m = 0; m < 4; ++m) {
;         const int row = row0 + ai * 128 + m * 16;
;         const int t = row - b * TT;
;         const bool isc = t >= TL;
;         float* dst = isc ? xc + ((size_t)b * TC + (t - TL)) * DM : xout + ((size_t)b * TL + t) * DM;
;         const float* src = src_input ? (isc ? cin + ((size_t)b * TC + (t - TL)) * DM : xin + ((size_t)b * TL + t) * DM) : dst;
;         const float* gate = modl + (size_t)(isc ? 16 : b) * 6144 + gi * DM;
; #pragma unroll
;         for (int bj = 0; bj < 2; ++bj) {
;           const int col = col0 + bj * 128;
; #pragma unroll
;           for (int n = 0; n < 2; ++n) {
;             pg8::f32x4 sv = *(const pg8::f32x4*)(src + col + 4 * n);
;             pg8::f32x4 gv = *(const pg8::f32x4*)(gate + col + 4 * n);
;             pg8::f32x4 o = sv + gv * acc[ai][bj][m][n];
;             *(pg8::f32x4*)(dst + col + 4 * n) = o;
;           }
;         }
;       }
;   }
	v_pk_fma_f32 v[98:99], v[98:99], v[204:205], v[162:163]
	v_pk_fma_f32 v[96:97], v[96:97], v[202:203], v[160:161]
	v_pk_fma_f32 v[94:95], v[94:95], v[208:209], v[166:167]
	v_pk_fma_f32 v[92:93], v[92:93], v[206:207], v[164:165]
	v_pk_fma_f32 v[86:87], v[86:87], v[212:213], v[170:171]
	v_pk_fma_f32 v[84:85], v[84:85], v[210:211], v[168:169]
	v_pk_fma_f32 v[74:75], v[74:75], v[216:217], v[180:181]
	v_pk_fma_f32 v[72:73], v[72:73], v[214:215], v[178:179]
	global_store_dwordx4 v[144:145], v[96:99], off sc1
	global_store_dwordx4 v[144:145], v[92:95], off offset:16 sc1
	global_store_dwordx4 v[144:145], v[84:87], off offset:512 sc1
	global_store_dwordx4 v[144:145], v[72:75], off offset:528 sc1
	global_load_dwordx4 v[160:163], v[150:151], off
	global_load_dwordx4 v[164:167], v[150:151], off offset:16
	global_load_dwordx4 v[168:171], v[150:151], off offset:512
	global_load_dwordx4 v[178:181], v[150:151], off offset:528
	s_waitcnt vmcnt(16)
	v_pk_fma_f32 v[82:83], v[82:83], v[204:205], v[220:221]
	v_pk_fma_f32 v[80:81], v[80:81], v[202:203], v[218:219]
	v_pk_fma_f32 v[78:79], v[78:79], v[208:209], v[224:225]
	v_pk_fma_f32 v[76:77], v[76:77], v[206:207], v[222:223]
	v_pk_fma_f32 v[70:71], v[70:71], v[212:213], v[228:229]
	v_pk_fma_f32 v[68:69], v[68:69], v[210:211], v[226:227]
	v_pk_fma_f32 v[66:67], v[66:67], v[216:217], v[232:233]
	v_pk_fma_f32 v[64:65], v[64:65], v[214:215], v[230:231]
	global_store_dwordx4 v[146:147], v[80:83], off sc1
	global_store_dwordx4 v[146:147], v[76:79], off offset:16 sc1
	global_store_dwordx4 v[146:147], v[68:71], off offset:512 sc1
	global_store_dwordx4 v[146:147], v[64:67], off offset:528 sc1
	global_load_dwordx4 v[218:221], v[192:193], off
	global_load_dwordx4 v[222:225], v[192:193], off offset:16
	global_load_dwordx4 v[226:229], v[192:193], off offset:512
	global_load_dwordx4 v[230:233], v[192:193], off offset:528
	s_waitcnt vmcnt(16)
	v_pk_fma_f32 v[62:63], v[62:63], v[204:205], v[236:237]
	v_pk_fma_f32 v[60:61], v[60:61], v[202:203], v[234:235]
	v_pk_fma_f32 v[58:59], v[58:59], v[208:209], v[240:241]
	v_pk_fma_f32 v[56:57], v[56:57], v[206:207], v[238:239]
	v_pk_fma_f32 v[54:55], v[54:55], v[212:213], v[244:245]
	v_pk_fma_f32 v[52:53], v[52:53], v[210:211], v[242:243]
	v_pk_fma_f32 v[42:43], v[42:43], v[216:217], v[248:249]
	v_pk_fma_f32 v[40:41], v[40:41], v[214:215], v[246:247]
	global_store_dwordx4 v[148:149], v[60:63], off sc1
	global_store_dwordx4 v[148:149], v[56:59], off offset:16 sc1
	global_store_dwordx4 v[148:149], v[52:55], off offset:512 sc1
	global_store_dwordx4 v[148:149], v[40:43], off offset:528 sc1
	global_load_dwordx4 v[234:237], v[194:195], off
	global_load_dwordx4 v[238:241], v[194:195], off offset:16
	global_load_dwordx4 v[242:245], v[194:195], off offset:512
	global_load_dwordx4 v[246:249], v[194:195], off offset:528
	s_waitcnt vmcnt(16)
	v_pk_fma_f32 v[50:51], v[50:51], v[204:205], v[162:163]
	v_pk_fma_f32 v[48:49], v[48:49], v[202:203], v[160:161]
	v_pk_fma_f32 v[46:47], v[46:47], v[208:209], v[166:167]
	v_pk_fma_f32 v[44:45], v[44:45], v[206:207], v[164:165]
	v_pk_fma_f32 v[38:39], v[38:39], v[212:213], v[170:171]
	v_pk_fma_f32 v[36:37], v[36:37], v[210:211], v[168:169]
	v_pk_fma_f32 v[26:27], v[26:27], v[216:217], v[180:181]
	v_pk_fma_f32 v[24:25], v[24:25], v[214:215], v[178:179]
	global_store_dwordx4 v[150:151], v[48:51], off sc1
	global_store_dwordx4 v[150:151], v[44:47], off offset:16 sc1
	global_store_dwordx4 v[150:151], v[36:39], off offset:512 sc1
	global_store_dwordx4 v[150:151], v[24:27], off offset:528 sc1
	s_waitcnt vmcnt(12)
	v_pk_fma_f32 v[34:35], v[34:35], v[204:205], v[220:221]
	v_pk_fma_f32 v[32:33], v[32:33], v[202:203], v[218:219]
	v_pk_fma_f32 v[30:31], v[30:31], v[208:209], v[224:225]
	v_pk_fma_f32 v[28:29], v[28:29], v[206:207], v[222:223]
	v_pk_fma_f32 v[22:23], v[22:23], v[212:213], v[228:229]
	v_pk_fma_f32 v[20:21], v[20:21], v[210:211], v[226:227]
	v_pk_fma_f32 v[10:11], v[10:11], v[216:217], v[232:233]
	v_pk_fma_f32 v[8:9], v[8:9], v[214:215], v[230:231]
	global_store_dwordx4 v[192:193], v[32:35], off sc1
	global_store_dwordx4 v[192:193], v[28:31], off offset:16 sc1
	global_store_dwordx4 v[192:193], v[20:23], off offset:512 sc1
	global_store_dwordx4 v[192:193], v[8:11], off offset:528 sc1
	s_waitcnt vmcnt(8)
	v_pk_fma_f32 v[18:19], v[18:19], v[204:205], v[236:237]
	v_pk_fma_f32 v[16:17], v[16:17], v[202:203], v[234:235]
	v_pk_fma_f32 v[14:15], v[14:15], v[208:209], v[240:241]
	v_pk_fma_f32 v[12:13], v[12:13], v[206:207], v[238:239]
	v_pk_fma_f32 v[6:7], v[6:7], v[212:213], v[244:245]
	v_pk_fma_f32 v[4:5], v[4:5], v[210:211], v[242:243]
	v_pk_fma_f32 v[2:3], v[2:3], v[216:217], v[248:249]
	v_pk_fma_f32 v[0:1], v[0:1], v[214:215], v[246:247]
	global_store_dwordx4 v[194:195], v[16:19], off sc1
	global_store_dwordx4 v[194:195], v[12:15], off offset:16 sc1
	global_store_dwordx4 v[194:195], v[4:7], off offset:512 sc1
	global_store_dwordx4 v[194:195], v[0:3], off offset:528 sc1
	s_and_b64 vcc, exec, s[2:3]
	s_mov_b64 s[2:3], -1
	s_cbranch_vccnz .LBB0_1496
	s_andn2_b64 vcc, exec, s[6:7]
	s_cbranch_vccnz .LBB0_1495
	s_barrier
	s_branch .LBB0_1495
